# layer-0 prologue: four row loads issued together with counted waits instead of load-wait-store x4
# speedup vs baseline: 1.0332x; 1.0007x over previous
; #define TIDX tid_opaque()
; __device__ __forceinline__ unsigned cvt_pk_bf16(float lo, float hi) { const f32x2_t v = {lo, hi}; const bf16x2_t b = __builtin_convertvector(v, bf16x2_t); return __builtin_bit_cast(unsigned, b); }
; __device__ void prep_phase(const float* x, float* h, bf16_t* hb, float* part) {
;     const int tid = TIDX, lane = tid & 63, gw = blockIdx.x * 8 + (tid >> 6), nw = gridDim.x * 8;
;     for (int row = gw; row < MT; row += nw) {
;         const f32x4* pr = (const f32x4*)(x + (size_t)row * DM); float ss = 0.f;
; #pragma unroll
;         for (int j = 0; j < 4; ++j) { const f32x4 v = pr[lane + 64 * j]; ss += v[0] * v[0] + v[1] * v[1] + v[2] * v[2] + v[3] * v[3];
;             ((f32x4*)(h + (size_t)row * DM))[lane + 64 * j] = v;
;             u32x2 w; w.x = cvt_pk_bf16(v[0], v[1]); w.y = cvt_pk_bf16(v[2], v[3]); ((u32x2*)(hb + (size_t)row * DM))[lane + 64 * j] = w; }
; #pragma unroll
;         for (int o = 32; o >= 1; o >>= 1) ss += __shfl_xor(ss, o);
;         if (lane < 16) part[(size_t)row * 16 + lane] = (lane == 0) ? ss : 0.f;
;     }
.LBB0_404:
	v_lshl_add_u64 v[26:27], s[6:7], 0, v[6:7]
	s_waitcnt lgkmcnt(0)
	global_load_dwordx4 v[14:17], v[26:27], off
	global_load_dwordx4 v[18:21], v[26:27], off offset:1024
	global_load_dwordx4 v[22:25], v[26:27], off offset:2048
	global_load_dwordx4 v[26:29], v[26:27], off offset:3072
	v_readlane_b32 s8, v255, 20
	v_readlane_b32 s9, v255, 21
	s_waitcnt vmcnt(3)
	v_cvt_pk_bf16_f32 v32, v14, v15
	v_lshl_add_u64 v[30:31], s[8:9], 0, v[6:7]
	v_cvt_pk_bf16_f32 v33, v16, v17
	global_store_dwordx4 v[30:31], v[14:17], off
	global_store_dwordx2 v[4:5], v[32:33], off
	v_mul_f32_e32 v1, v15, v15
	v_fmac_f32_e32 v1, v14, v14
	v_fmac_f32_e32 v1, v16, v16
	v_fmac_f32_e32 v1, v17, v17
	s_waitcnt vmcnt(4)
	v_cvt_pk_bf16_f32 v32, v18, v19
	v_cvt_pk_bf16_f32 v33, v20, v21
	global_store_dwordx4 v[30:31], v[18:21], off offset:1024
	global_store_dwordx2 v[4:5], v[32:33], off offset:512
	v_mul_f32_e32 v14, v19, v19
	v_fmac_f32_e32 v14, v18, v18
	v_fmac_f32_e32 v14, v20, v20
	v_fmac_f32_e32 v14, v21, v21
	v_add_f32_e32 v1, v1, v14
	s_waitcnt vmcnt(5)
	v_cvt_pk_bf16_f32 v32, v22, v23
	v_cvt_pk_bf16_f32 v33, v24, v25
	global_store_dwordx4 v[30:31], v[22:25], off offset:2048
	global_store_dwordx2 v[4:5], v[32:33], off offset:1024
	v_mul_f32_e32 v14, v23, v23
	v_fmac_f32_e32 v14, v22, v22
	v_fmac_f32_e32 v14, v24, v24
	v_fmac_f32_e32 v14, v25, v25
	v_add_f32_e32 v1, v1, v14
	s_waitcnt vmcnt(6)
	v_mul_f32_e32 v14, v27, v27
	v_fmac_f32_e32 v14, v26, v26
	v_fmac_f32_e32 v14, v28, v28
	v_fmac_f32_e32 v14, v29, v29
	v_add_f32_e32 v1, v1, v14
	ds_bpermute_b32 v14, v8, v1
	v_cvt_pk_bf16_f32 v16, v26, v27
	v_cvt_pk_bf16_f32 v17, v28, v29
	global_store_dwordx4 v[30:31], v[26:29], off offset:3072
	global_store_dwordx2 v[4:5], v[16:17], off offset:1536
	s_waitcnt lgkmcnt(0)
	v_add_f32_e32 v1, v1, v14
	ds_bpermute_b32 v14, v9, v1
	s_waitcnt lgkmcnt(0)
	v_add_f32_e32 v1, v1, v14
	ds_bpermute_b32 v14, v10, v1
	s_waitcnt lgkmcnt(0)
	v_add_f32_e32 v1, v1, v14
	ds_bpermute_b32 v14, v11, v1
	s_waitcnt lgkmcnt(0)
	v_add_f32_e32 v1, v1, v14
	ds_bpermute_b32 v14, v12, v1
	s_waitcnt lgkmcnt(0)
	v_add_f32_e32 v1, v1, v14
	ds_bpermute_b32 v14, v13, v1
	s_and_saveexec_b64 s[8:9], vcc
	s_cbranch_execz .LBB0_403
	s_waitcnt lgkmcnt(0)
	v_add_f32_e32 v1, v1, v14
	v_cndmask_b32_e64 v1, 0, v1, s[0:1]
	global_store_dword v[2:3], v1, off
	s_branch .LBB0_403
